# second compression layer (cmp2 phase): the VALU f32 multiply-add loop replaced by v_mfma_f32_16x16x4_f32 (f32 operands, f32 accumulate; 8 waves = 4 column blocks x 2 K halves, partial sums combined th
# speedup vs baseline: 1.0073x; 1.0054x over previous
.LBB0_43:
	s_barrier
	global_load_dwordx4 v[76:79], v[28:29], off
	global_load_dwordx4 v[80:83], v[30:31], off
	global_load_dwordx4 v[84:87], v[32:33], off
	global_load_dwordx4 v[88:91], v[34:35], off
	global_load_dwordx4 v[92:95], v[36:37], off
	global_load_dwordx4 v[96:99], v[38:39], off
	global_load_dwordx4 v[100:103], v[40:41], off
	global_load_dwordx4 v[104:107], v[42:43], off
	s_lshl_b32 s10, s3, 4
	v_add_u32_e32 v47, s10, v53
	v_bfe_u32 v48, v47, 2, 7
	v_cmp_ne_u32_e32 vcc, s56, v48
	v_mov_b32_e32 v46, 0
	v_mov_b32_e32 v0, 0
	v_mov_b32_e32 v1, 0
	v_mov_b32_e32 v2, 0
	v_mov_b32_e32 v3, 0
	s_and_saveexec_b64 s[8:9], vcc
	s_cbranch_execz .LBB0_45
	v_ashrrev_i32_e32 v0, 9, v47
	v_mad_i32_i24 v0, v0, s56, v48
	v_lshl_or_b32 v0, v0, 2, v54
	v_ashrrev_i32_e32 v1, 31, v0
	v_lshlrev_b64 v[0:1], 9, v[0:1]
	v_lshl_add_u64 v[0:1], v[44:45], 0, v[0:1]
	global_load_dwordx4 v[0:3], v[0:1], off
.LBB0_45:
	s_or_b64 exec, exec, s[8:9]
	s_waitcnt vmcnt(0)
	ds_write_b128 v52, v[76:79]
	ds_write_b128 v52, v[80:83] offset:8192
	ds_write_b128 v52, v[84:87] offset:16384
	ds_write_b128 v52, v[88:91] offset:24576
	ds_write_b128 v52, v[92:95] offset:32768
	ds_write_b128 v52, v[96:99] offset:40960
	ds_write_b128 v52, v[100:103] offset:49152
	ds_write_b128 v52, v[104:107] offset:57344
	ds_write_b128 v56, v[0:3]
	s_waitcnt lgkmcnt(0)
	s_barrier
	v_and_b32_e32 v0, 15, v4
	v_lshrrev_b32_e32 v1, 4, v4
	v_ashrrev_i32_e32 v2, 6, v162
	v_lshrrev_b32_e32 v3, 2, v2
	v_and_b32_e32 v2, 3, v2
	v_lshlrev_b32_e32 v57, 9, v0
	v_lshl_add_u32 v57, v3, 8, v57
	v_lshl_add_u32 v57, v1, 1, v57
	v_add_u32_e32 v57, 0x10000, v57
	v_lshlrev_b32_e32 v58, 15, v3
	v_lshl_add_u32 v58, v1, 8, v58
	v_lshl_add_u32 v58, v2, 6, v58
	v_lshl_add_u32 v58, v0, 2, v58
	v_lshlrev_b32_e32 v59, 12, v3
	v_lshl_add_u32 v59, v1, 10, v59
	v_lshl_add_u32 v59, v2, 6, v59
	v_lshl_add_u32 v59, v0, 2, v59
	v_add_u32_e32 v59, 0x12000, v59
	v_mov_b32_e32 v60, 0
	v_mov_b32_e32 v61, 0
	v_mov_b32_e32 v62, 0
	v_mov_b32_e32 v63, 0
	ds_read_u16 v64, v57 offset:0
	ds_read_u16 v65, v57 offset:8
	ds_read_u16 v66, v57 offset:16
	ds_read_u16 v67, v57 offset:24
	ds_read_u16 v68, v57 offset:32
	ds_read_u16 v69, v57 offset:40
	ds_read_u16 v70, v57 offset:48
	ds_read_u16 v71, v57 offset:56
	ds_read_b32 v72, v58 offset:0
	ds_read_b32 v73, v58 offset:1024
	ds_read_b32 v0, v58 offset:2048
	ds_read_b32 v1, v58 offset:3072
	ds_read_b32 v2, v58 offset:4096
	ds_read_b32 v3, v58 offset:5120
	ds_read_b32 v46, v58 offset:6144
	ds_read_b32 v47, v58 offset:7168
	s_waitcnt lgkmcnt(0)
	v_lshlrev_b32_e32 v64, 16, v64
	v_lshlrev_b32_e32 v65, 16, v65
	v_lshlrev_b32_e32 v66, 16, v66
	v_lshlrev_b32_e32 v67, 16, v67
	v_lshlrev_b32_e32 v68, 16, v68
	v_lshlrev_b32_e32 v69, 16, v69
	v_lshlrev_b32_e32 v70, 16, v70
	v_lshlrev_b32_e32 v71, 16, v71
	v_mfma_f32_16x16x4_f32 v[60:63], v64, v72, v[60:63]
	v_mfma_f32_16x16x4_f32 v[60:63], v65, v73, v[60:63]
	v_mfma_f32_16x16x4_f32 v[60:63], v66, v0, v[60:63]
	v_mfma_f32_16x16x4_f32 v[60:63], v67, v1, v[60:63]
	v_mfma_f32_16x16x4_f32 v[60:63], v68, v2, v[60:63]
	v_mfma_f32_16x16x4_f32 v[60:63], v69, v3, v[60:63]
	v_mfma_f32_16x16x4_f32 v[60:63], v70, v46, v[60:63]
	v_mfma_f32_16x16x4_f32 v[60:63], v71, v47, v[60:63]
	ds_read_u16 v64, v57 offset:64
	ds_read_u16 v65, v57 offset:72
	ds_read_u16 v66, v57 offset:80
	ds_read_u16 v67, v57 offset:88
	ds_read_u16 v68, v57 offset:96
	ds_read_u16 v69, v57 offset:104
	ds_read_u16 v70, v57 offset:112
	ds_read_u16 v71, v57 offset:120
	ds_read_b32 v72, v58 offset:8192
	ds_read_b32 v73, v58 offset:9216
	ds_read_b32 v0, v58 offset:10240
	ds_read_b32 v1, v58 offset:11264
	ds_read_b32 v2, v58 offset:12288
	ds_read_b32 v3, v58 offset:13312
	ds_read_b32 v46, v58 offset:14336
	ds_read_b32 v47, v58 offset:15360
	s_waitcnt lgkmcnt(0)
	v_lshlrev_b32_e32 v64, 16, v64
	v_lshlrev_b32_e32 v65, 16, v65
	v_lshlrev_b32_e32 v66, 16, v66
	v_lshlrev_b32_e32 v67, 16, v67
	v_lshlrev_b32_e32 v68, 16, v68
	v_lshlrev_b32_e32 v69, 16, v69
	v_lshlrev_b32_e32 v70, 16, v70
	v_lshlrev_b32_e32 v71, 16, v71
	v_mfma_f32_16x16x4_f32 v[60:63], v64, v72, v[60:63]
	v_mfma_f32_16x16x4_f32 v[60:63], v65, v73, v[60:63]
	v_mfma_f32_16x16x4_f32 v[60:63], v66, v0, v[60:63]
	v_mfma_f32_16x16x4_f32 v[60:63], v67, v1, v[60:63]
	v_mfma_f32_16x16x4_f32 v[60:63], v68, v2, v[60:63]
	v_mfma_f32_16x16x4_f32 v[60:63], v69, v3, v[60:63]
	v_mfma_f32_16x16x4_f32 v[60:63], v70, v46, v[60:63]
	v_mfma_f32_16x16x4_f32 v[60:63], v71, v47, v[60:63]
	ds_read_u16 v64, v57 offset:128
	ds_read_u16 v65, v57 offset:136
	ds_read_u16 v66, v57 offset:144
	ds_read_u16 v67, v57 offset:152
	ds_read_u16 v68, v57 offset:160
	ds_read_u16 v69, v57 offset:168
	ds_read_u16 v70, v57 offset:176
	ds_read_u16 v71, v57 offset:184
	ds_read_b32 v72, v58 offset:16384
	ds_read_b32 v73, v58 offset:17408
	ds_read_b32 v0, v58 offset:18432
	ds_read_b32 v1, v58 offset:19456
	ds_read_b32 v2, v58 offset:20480
	ds_read_b32 v3, v58 offset:21504
	ds_read_b32 v46, v58 offset:22528
	ds_read_b32 v47, v58 offset:23552
	s_waitcnt lgkmcnt(0)
	v_lshlrev_b32_e32 v64, 16, v64
	v_lshlrev_b32_e32 v65, 16, v65
	v_lshlrev_b32_e32 v66, 16, v66
	v_lshlrev_b32_e32 v67, 16, v67
	v_lshlrev_b32_e32 v68, 16, v68
	v_lshlrev_b32_e32 v69, 16, v69
	v_lshlrev_b32_e32 v70, 16, v70
	v_lshlrev_b32_e32 v71, 16, v71
	v_mfma_f32_16x16x4_f32 v[60:63], v64, v72, v[60:63]
	v_mfma_f32_16x16x4_f32 v[60:63], v65, v73, v[60:63]
	v_mfma_f32_16x16x4_f32 v[60:63], v66, v0, v[60:63]
	v_mfma_f32_16x16x4_f32 v[60:63], v67, v1, v[60:63]
	v_mfma_f32_16x16x4_f32 v[60:63], v68, v2, v[60:63]
	v_mfma_f32_16x16x4_f32 v[60:63], v69, v3, v[60:63]
	v_mfma_f32_16x16x4_f32 v[60:63], v70, v46, v[60:63]
	v_mfma_f32_16x16x4_f32 v[60:63], v71, v47, v[60:63]
	ds_read_u16 v64, v57 offset:192
	ds_read_u16 v65, v57 offset:200
	ds_read_u16 v66, v57 offset:208
	ds_read_u16 v67, v57 offset:216
	ds_read_u16 v68, v57 offset:224
	ds_read_u16 v69, v57 offset:232
	ds_read_u16 v70, v57 offset:240
	ds_read_u16 v71, v57 offset:248
	ds_read_b32 v72, v58 offset:24576
	ds_read_b32 v73, v58 offset:25600
	ds_read_b32 v0, v58 offset:26624
	ds_read_b32 v1, v58 offset:27648
	ds_read_b32 v2, v58 offset:28672
	ds_read_b32 v3, v58 offset:29696
	ds_read_b32 v46, v58 offset:30720
	ds_read_b32 v47, v58 offset:31744
	s_waitcnt lgkmcnt(0)
	v_lshlrev_b32_e32 v64, 16, v64
	v_lshlrev_b32_e32 v65, 16, v65
	v_lshlrev_b32_e32 v66, 16, v66
	v_lshlrev_b32_e32 v67, 16, v67
	v_lshlrev_b32_e32 v68, 16, v68
	v_lshlrev_b32_e32 v69, 16, v69
	v_lshlrev_b32_e32 v70, 16, v70
	v_lshlrev_b32_e32 v71, 16, v71
	v_mfma_f32_16x16x4_f32 v[60:63], v64, v72, v[60:63]
	v_mfma_f32_16x16x4_f32 v[60:63], v65, v73, v[60:63]
	v_mfma_f32_16x16x4_f32 v[60:63], v66, v0, v[60:63]
	v_mfma_f32_16x16x4_f32 v[60:63], v67, v1, v[60:63]
	v_mfma_f32_16x16x4_f32 v[60:63], v68, v2, v[60:63]
	v_mfma_f32_16x16x4_f32 v[60:63], v69, v3, v[60:63]
	v_mfma_f32_16x16x4_f32 v[60:63], v70, v46, v[60:63]
	v_mfma_f32_16x16x4_f32 v[60:63], v71, v47, v[60:63]
	s_nop 7
	s_nop 7
	s_nop 7
	ds_write_b32 v59, v60
	ds_write_b32 v59, v61 offset:256
	ds_write_b32 v59, v62 offset:512
	ds_write_b32 v59, v63 offset:768
	s_waitcnt lgkmcnt(0)
	s_barrier
	v_ashrrev_i32_e32 v0, 6, v162
	v_lshl_add_u32 v0, v0, 9, v55
	v_add_u32_e32 v0, 0x12000, v0
	ds_read_b32 v46, v0
	ds_read_b32 v1, v0 offset:4096
	ds_read_b32 v47, v0 offset:256
	ds_read_b32 v2, v0 offset:4352
	s_waitcnt lgkmcnt(0)
	v_add_f32_e32 v46, v46, v1
	v_add_f32_e32 v47, v47, v2
	v_add_u32_e32 v59, s10, v50
	v_lshrrev_b32_e32 v0, 2, v59
	v_and_b32_e32 v57, 0x7f, v0
	v_cmp_eq_u32_e64 s[10:11], s56, v57
	v_cmp_ne_u32_e64 s[8:9], s56, v57
	s_mov_b64 s[18:19], -1
	s_and_b64 vcc, exec, s[14:15]
	s_cbranch_vccz .LBB0_49
	v_cvt_pk_bf16_f32 v0, v46, s0
	v_cndmask_b32_e64 v60, v0, 0, s[10:11]
	s_mov_b64 s[18:19], 0

.LBB0_276:
	s_add_u32 s3, s20, 0x100
	s_addc_u32 s34, s21, 0
	s_add_u32 s8, s30, 0x80
	v_mov_b64_e32 v[0:1], 0
	v_mov_b64_e32 v[2:3], 0
	v_mov_b64_e32 v[4:5], 0
	v_mov_b64_e32 v[6:7], 0
	v_mov_b64_e32 v[8:9], 0
	v_mov_b64_e32 v[10:11], 0
	v_mov_b64_e32 v[12:13], 0
	v_mov_b64_e32 v[14:15], 0
	v_mov_b64_e32 v[16:17], 0
	v_mov_b64_e32 v[18:19], 0
	v_mov_b64_e32 v[20:21], 0
	v_mov_b64_e32 v[22:23], 0
	v_mov_b64_e32 v[24:25], 0
	v_mov_b64_e32 v[26:27], 0
	v_mov_b64_e32 v[28:29], 0
	v_mov_b64_e32 v[30:31], 0
	v_mov_b64_e32 v[32:33], 0
	v_mov_b64_e32 v[34:35], 0
	v_mov_b64_e32 v[36:37], 0
	v_mov_b64_e32 v[38:39], 0
	v_mov_b64_e32 v[40:41], 0
	v_mov_b64_e32 v[42:43], 0
	v_mov_b64_e32 v[44:45], 0
	v_mov_b64_e32 v[46:47], 0
	v_mov_b64_e32 v[48:49], 0
	v_mov_b64_e32 v[50:51], 0
	v_mov_b64_e32 v[52:53], 0
	v_mov_b64_e32 v[54:55], 0
	v_mov_b64_e32 v[56:57], 0
	v_mov_b64_e32 v[58:59], 0
	v_mov_b64_e32 v[60:61], 0
	v_mov_b64_e32 v[62:63], 0
	v_mov_b64_e32 v[64:65], 0
	v_mov_b64_e32 v[66:67], 0
	v_mov_b64_e32 v[68:69], 0
	v_mov_b64_e32 v[70:71], 0
	v_mov_b64_e32 v[72:73], 0
	v_mov_b64_e32 v[74:75], 0
	v_mov_b64_e32 v[76:77], 0
	v_mov_b64_e32 v[78:79], 0
	v_mov_b64_e32 v[80:81], 0
	v_mov_b64_e32 v[82:83], 0
	v_mov_b64_e32 v[84:85], 0
	v_mov_b64_e32 v[86:87], 0
	v_mov_b64_e32 v[88:89], 0
	v_mov_b64_e32 v[90:91], 0
	v_mov_b64_e32 v[92:93], 0
	v_mov_b64_e32 v[94:95], 0
	v_mov_b64_e32 v[96:97], 0
	v_mov_b64_e32 v[98:99], 0
	v_mov_b64_e32 v[100:101], 0
	v_mov_b64_e32 v[102:103], 0
	v_mov_b64_e32 v[104:105], 0
	v_mov_b64_e32 v[106:107], 0
	v_mov_b64_e32 v[108:109], 0
	v_mov_b64_e32 v[110:111], 0
	v_mov_b64_e32 v[112:113], 0
	v_mov_b64_e32 v[114:115], 0
	v_mov_b64_e32 v[116:117], 0
	v_mov_b64_e32 v[118:119], 0
	v_mov_b64_e32 v[120:121], 0
	v_mov_b64_e32 v[122:123], 0
	v_mov_b64_e32 v[124:125], 0
	v_mov_b64_e32 v[126:127], 0
	s_addc_u32 s9, s31, 0
	s_mov_b32 s20, 0
	s_waitcnt vmcnt(0)
	s_nop 0
	s_nop 0
	s_nop 0
	s_nop 0
	s_nop 0
	s_nop 0
	s_nop 0
	s_nop 0
	s_nop 0
	s_nop 0
	s_nop 0
	s_nop 0
	s_nop 0
	s_nop 0
	s_nop 0
	s_nop 0
	s_nop 0
	s_nop 0
	s_nop 0
	s_nop 0
	s_nop 0
	s_nop 0
	s_nop 0
	s_nop 0
	s_nop 0
	s_nop 0
	s_nop 0
	s_nop 0
	s_nop 0
	s_nop 0
	s_nop 0
	s_nop 0
	s_nop 0
	s_nop 0
	s_nop 0
	s_nop 0
	s_nop 0
	s_nop 0
	s_nop 0
	s_nop 0
	s_nop 0
	s_nop 0
	s_nop 0
	s_nop 0
	s_nop 0
	s_nop 0
	s_nop 0
	s_nop 0
	s_nop 0
	s_nop 0
	s_nop 0
	s_nop 0
	s_nop 0
	s_nop 0
	s_nop 0
	s_nop 0
	s_nop 0
	s_nop 0
	s_nop 0
	s_nop 0
	s_nop 0
	s_nop 0
	s_nop 0
